# up-gemm-b0-fragment-reads-moved-to-read-free-phases
# speedup vs baseline: 1.0029x; 1.0022x over previous
; #define PG8_STAGE(bufoff, gbase, hoff, imm) do { _Pragma("unroll") for (int _i = 0; _i < 2; ++_i) { \
;         asm volatile("s_mov_b32 m0, %0\n\ts_nop 0\n\tglobal_load_lds_dwordx4 %1, %2" \
;             :: "s"(lds0 + (unsigned)((bufoff) + _i * 8192)), "v"(voff0), "s"((const char*)(gbase) + (size_t)(hoff) + (size_t)(_i * 8192)) : "memory"); } } while (0)
; #define PG8_LDA(dst, b, h) do { _Pragma("unroll") for (int m = 0; m < 4; ++m) _Pragma("unroll") for (int k = 0; k < 2; ++k) dst[m][k] = *(const LAS bf16x8*)(lds + PG8_SA(b, h) + aoff + m * 2048 + k * 1024); } while (0)
; #define PG8_LDB(dst, b, h) do { _Pragma("unroll") for (int n = 0; n < 2; ++n) _Pragma("unroll") for (int k = 0; k < 2; ++k) dst[n][k] = *(const LAS bf16x8*)(lds + PG8_SB(b, h) + boff + n * 2048 + k * 1024); } while (0)
; #define PG8_WAIT_L(n) asm volatile("s_waitcnt lgkmcnt(" #n ")" ::: "memory")
; #define PG8_BAR __builtin_amdgcn_s_barrier()
; #define PG8_SCHED __builtin_amdgcn_sched_barrier(0)
; template <class Epi>
; __device__ __forceinline__ void gemm_phase(LAS unsigned char* lds, const Gemm g, const StaticOrder& S, const Epi& E) {
;     ...
;         const bool has_next = S.next(ui + 1, nxt);
;         const char* nA = has_next ? (const char*)g.A + (size_t)nxt.pm * tstepA + (size_t)(nxt.pn >> g.gshift) * g.gstride : cA;
;         const char* nB = has_next ? (const char*)g.Bt + (size_t)nxt.pn * tstepB : cB;
;         for (int t = 0; t < nt; t += 2) {
;             const bool last = (t == nt - 2);
;             if (last) E.pre(cur, wid, lane, (unsigned)(size_t)(lds + STAGE_BYTES));
;             const char* aT = cA + (size_t)t * KS;
;             const char* a2 = last ? nA : aT + 2 * KS; const char* b2 = last ? nB : cB + (size_t)(t + 2) * KS;
;             PG8_LDB(B0, 0, 0); PG8_SCHED; PG8_LDA(At, 0, 0); PG8_STAGE(PG8_SA(1, 1), aT + KS, hA, 0);
;             PG8_WAIT_L(8); PG8_BAR; PG8_WAIT_L(0); PG8_MMA(0, 0, At, B0); PG8_BAR; PG8_SCHED;
;     ...
; #pragma unroll
;         for (int a = 0; a < 2; ++a)
; #pragma unroll
;             for (int b = 0; b < 2; ++b)
; #pragma unroll
;                 for (int m = 0; m < 4; ++m)
; #pragma unroll
;                     for (int n = 0; n < 2; ++n) acc[a][b][m][n] = (f32x4){0.f, 0.f, 0.f, 0.f};
;         cur = nxt; cA = nA; cB = nB; ++ui;
.LBB0_737:
	s_ashr_i32 s71, s70, 31
	v_cmp_lt_i64_e32 vcc, s[8:9], v[198:199]
	s_lshl_b64 s[8:9], s[70:71], 20
	s_add_u32 s72, s26, s8
	s_addc_u32 s73, s27, s9
	s_and_b64 s[8:9], vcc, exec
	s_cselect_b32 s50, s73, s77
	s_cselect_b32 s51, s72, s76
	s_ashr_i32 s69, s68, 31
	s_lshl_b64 s[8:9], s[68:69], 20
	s_add_u32 s74, s84, s8
	s_addc_u32 s75, s85, s9
	s_and_b64 s[8:9], vcc, exec
	s_cselect_b32 s69, s75, s79
	s_cselect_b32 s0, s74, s78
	s_lshl_b32 s8, s1, 7
	s_ashr_i32 s9, s8, 31
	s_lshl_b64 s[10:11], s[8:9], 2
	s_add_u32 s10, s96, s10
	s_addc_u32 s11, s30, s11
	s_add_u32 s1, s78, 0x8000
	v_mov_b32_e32 v12, 0
	s_addc_u32 s9, s79, 0
	s_mov_b32 s71, -2
	v_mov_b32_e32 v13, v12
	v_mov_b32_e32 v14, v12
	v_mov_b32_e32 v15, v12
	v_mov_b32_e32 v44, v12
	v_mov_b32_e32 v45, v12
	v_mov_b32_e32 v46, v12
	v_mov_b32_e32 v47, v12
	v_mov_b32_e32 v8, v12
	v_mov_b32_e32 v9, v12
	v_mov_b32_e32 v10, v12
	v_mov_b32_e32 v11, v12
	v_mov_b32_e32 v40, v12
	v_mov_b32_e32 v41, v12
	v_mov_b32_e32 v42, v12
	v_mov_b32_e32 v43, v12
	v_mov_b32_e32 v4, v12
	v_mov_b32_e32 v5, v12
	v_mov_b32_e32 v6, v12
	v_mov_b32_e32 v7, v12
	v_mov_b32_e32 v36, v12
	v_mov_b32_e32 v37, v12
	v_mov_b32_e32 v38, v12
	v_mov_b32_e32 v39, v12
	v_mov_b32_e32 v0, v12
	v_mov_b32_e32 v1, v12
	v_mov_b32_e32 v2, v12
	v_mov_b32_e32 v3, v12
	v_mov_b32_e32 v32, v12
	v_mov_b32_e32 v33, v12
	v_mov_b32_e32 v34, v12
	v_mov_b32_e32 v35, v12
	v_mov_b32_e32 v76, v12
	v_mov_b32_e32 v77, v12
	v_mov_b32_e32 v78, v12
	v_mov_b32_e32 v79, v12
	v_mov_b32_e32 v112, v12
	v_mov_b32_e32 v113, v12
	v_mov_b32_e32 v114, v12
	v_mov_b32_e32 v115, v12
	v_mov_b32_e32 v72, v12
	v_mov_b32_e32 v73, v12
	v_mov_b32_e32 v74, v12
	v_mov_b32_e32 v75, v12
	v_mov_b32_e32 v108, v12
	v_mov_b32_e32 v109, v12
	v_mov_b32_e32 v110, v12
	v_mov_b32_e32 v111, v12
	v_mov_b32_e32 v68, v12
	v_mov_b32_e32 v69, v12
	v_mov_b32_e32 v70, v12
	v_mov_b32_e32 v71, v12
	v_mov_b32_e32 v104, v12
	v_mov_b32_e32 v105, v12
	v_mov_b32_e32 v106, v12
	v_mov_b32_e32 v107, v12
	v_mov_b32_e32 v64, v12
	v_mov_b32_e32 v65, v12
	v_mov_b32_e32 v66, v12
	v_mov_b32_e32 v67, v12
	v_mov_b32_e32 v100, v12
	v_mov_b32_e32 v101, v12
	v_mov_b32_e32 v102, v12
	v_mov_b32_e32 v103, v12
	v_mov_b32_e32 v28, v12
	v_mov_b32_e32 v29, v12
	v_mov_b32_e32 v30, v12
	v_mov_b32_e32 v31, v12
	v_mov_b32_e32 v60, v12
	v_mov_b32_e32 v61, v12
	v_mov_b32_e32 v62, v12
	v_mov_b32_e32 v63, v12
	v_mov_b32_e32 v24, v12
	v_mov_b32_e32 v25, v12
	v_mov_b32_e32 v26, v12
	v_mov_b32_e32 v27, v12
	v_mov_b32_e32 v56, v12
	v_mov_b32_e32 v57, v12
	v_mov_b32_e32 v58, v12
	v_mov_b32_e32 v59, v12
	v_mov_b32_e32 v20, v12
	v_mov_b32_e32 v21, v12
	v_mov_b32_e32 v22, v12
	v_mov_b32_e32 v23, v12
	v_mov_b32_e32 v52, v12
	v_mov_b32_e32 v53, v12
	v_mov_b32_e32 v54, v12
	v_mov_b32_e32 v55, v12
	v_mov_b32_e32 v16, v12
	v_mov_b32_e32 v17, v12
	v_mov_b32_e32 v18, v12
	v_mov_b32_e32 v19, v12
	v_mov_b32_e32 v48, v12
	v_mov_b32_e32 v49, v12
	v_mov_b32_e32 v50, v12
	v_mov_b32_e32 v51, v12
	v_mov_b32_e32 v96, v12
	v_mov_b32_e32 v97, v12
	v_mov_b32_e32 v98, v12
	v_mov_b32_e32 v99, v12
	v_mov_b32_e32 v124, v12
	v_mov_b32_e32 v125, v12
	v_mov_b32_e32 v126, v12
	v_mov_b32_e32 v127, v12
	v_mov_b32_e32 v92, v12
	v_mov_b32_e32 v93, v12
	v_mov_b32_e32 v94, v12
	v_mov_b32_e32 v95, v12
	v_mov_b32_e32 v120, v12
	v_mov_b32_e32 v121, v12
	v_mov_b32_e32 v122, v12
	v_mov_b32_e32 v123, v12
	v_mov_b32_e32 v84, v12
	v_mov_b32_e32 v85, v12
	v_mov_b32_e32 v86, v12
	v_mov_b32_e32 v87, v12
	v_mov_b32_e32 v88, v12
	v_mov_b32_e32 v89, v12
	v_mov_b32_e32 v90, v12
	v_mov_b32_e32 v91, v12
	v_mov_b32_e32 v80, v12
	v_mov_b32_e32 v81, v12
	v_mov_b32_e32 v82, v12
	v_mov_b32_e32 v83, v12
	v_mov_b32_e32 v116, v12
	v_mov_b32_e32 v117, v12
	v_mov_b32_e32 v118, v12
	v_mov_b32_e32 v119, v12
	v_add_u32_e32 v140, 0x10000, v177
	ds_read_b128 v[128:131], v140
	ds_read_b128 v[132:135], v140 offset:1024
	ds_read_b128 v[136:139], v140 offset:2048
	ds_read_b128 v[140:143], v140 offset:3072
	s_branch .LBB0_739
.LBB0_738:
	s_add_u32 s78, s76, 0x8000
	s_addc_u32 s79, s77, 0
	s_and_b64 s[48:49], s[82:83], exec
	s_cselect_b32 s81, s50, s79
	s_cselect_b32 s80, s51, s78
	ds_read_b128 v[144:147], v178
	ds_read_b128 v[148:151], v178 offset:1024
	ds_read_b128 v[184:187], v178 offset:2048
	ds_read_b128 v[200:203], v178 offset:3072
	ds_read_b128 v[204:207], v178 offset:4096
	ds_read_b128 v[208:211], v178 offset:5120
	ds_read_b128 v[212:215], v178 offset:6144
	ds_read_b128 v[236:239], v178 offset:7168
	s_waitcnt lgkmcnt(8)
	s_waitcnt vmcnt(10)
	s_barrier
	s_waitcnt lgkmcnt(0)
	s_waitcnt lgkmcnt(7)
	v_mfma_f32_16x16x32_bf16 v[116:119], v[128:131], v[144:147], v[116:119]
	v_mfma_f32_16x16x32_bf16 v[80:83], v[136:139], v[144:147], v[80:83]
	s_waitcnt lgkmcnt(5)
	v_mfma_f32_16x16x32_bf16 v[88:91], v[128:131], v[184:187], v[88:91]
	v_mfma_f32_16x16x32_bf16 v[84:87], v[136:139], v[184:187], v[84:87]
	s_waitcnt lgkmcnt(3)
	v_mfma_f32_16x16x32_bf16 v[120:123], v[128:131], v[204:207], v[120:123]
	v_mfma_f32_16x16x32_bf16 v[92:95], v[136:139], v[204:207], v[92:95]
	s_waitcnt lgkmcnt(1)
	v_mfma_f32_16x16x32_bf16 v[124:127], v[128:131], v[212:215], v[124:127]
	v_mfma_f32_16x16x32_bf16 v[96:99], v[136:139], v[212:215], v[96:99]
	v_mfma_f32_16x16x32_bf16 v[116:119], v[132:135], v[148:151], v[116:119]
	v_mfma_f32_16x16x32_bf16 v[80:83], v[140:143], v[148:151], v[80:83]
	v_mfma_f32_16x16x32_bf16 v[88:91], v[132:135], v[200:203], v[88:91]
	v_mfma_f32_16x16x32_bf16 v[84:87], v[140:143], v[200:203], v[84:87]
	v_mfma_f32_16x16x32_bf16 v[120:123], v[132:135], v[208:211], v[120:123]
	v_mfma_f32_16x16x32_bf16 v[92:95], v[140:143], v[208:211], v[92:95]
	s_waitcnt lgkmcnt(0)
	v_mfma_f32_16x16x32_bf16 v[124:127], v[132:135], v[236:239], v[124:127]
	v_mfma_f32_16x16x32_bf16 v[96:99], v[140:143], v[236:239], v[96:99]
	s_barrier
; #define PG8_STAGE(bufoff, gbase, hoff, imm) do { _Pragma("unroll") for (int _i = 0; _i < 2; ++_i) { \
;         asm volatile("s_mov_b32 m0, %0\n\ts_nop 0\n\tglobal_load_lds_dwordx4 %1, %2" \
;             :: "s"(lds0 + (unsigned)((bufoff) + _i * 8192)), "v"(voff0), "s"((const char*)(gbase) + (size_t)(hoff) + (size_t)(_i * 8192)) : "memory"); } } while (0)
; #define PG8_LDA(dst, b, h) do { _Pragma("unroll") for (int m = 0; m < 4; ++m) _Pragma("unroll") for (int k = 0; k < 2; ++k) dst[m][k] = *(const LAS bf16x8*)(lds + PG8_SA(b, h) + aoff + m * 2048 + k * 1024); } while (0)
; #define PG8_LDB(dst, b, h) do { _Pragma("unroll") for (int n = 0; n < 2; ++n) _Pragma("unroll") for (int k = 0; k < 2; ++k) dst[n][k] = *(const LAS bf16x8*)(lds + PG8_SB(b, h) + boff + n * 2048 + k * 1024); } while (0)
; #define PG8_MMA(ai, bj, At, Bt) do { __builtin_amdgcn_s_setprio(1); _Pragma("unroll") for (int m = 0; m < 4; ++m) _Pragma("unroll") for (int n = 0; n < 2; ++n) _Pragma("unroll") for (int k = 0; k < 2; ++k) \
;         acc[ai][bj][m][n] = __builtin_amdgcn_mfma_f32_16x16x32_bf16(Bt[n][k], At[m][k], acc[ai][bj][m][n], 0, 0, 0); __builtin_amdgcn_s_setprio(0); } while (0)
; #define PG8_WAIT_V(n) asm volatile("s_waitcnt vmcnt(" #n ")" ::: "memory")
; #define PG8_WAIT_L(n) asm volatile("s_waitcnt lgkmcnt(" #n ")" ::: "memory")
; #define PG8_BAR __builtin_amdgcn_s_barrier()
; #define PG8_SCHED __builtin_amdgcn_sched_barrier(0)
; template <class Epi>
; __device__ __forceinline__ void gemm_phase(LAS unsigned char* lds, const Gemm g, const StaticOrder& S, const Epi& E) {
;     ...
;             PG8_LDB(B1, 0, 1); PG8_STAGE(PG8_SB(0, 0), b2, 0, 0);
;             PG8_BAR; PG8_WAIT_L(0); PG8_MMA(0, 1, At, B1); PG8_BAR;
;             PG8_LDA(At, 0, 1); PG8_STAGE(PG8_SA(0, 0), a2, 0, 0);
;             PG8_BAR; PG8_WAIT_L(0); PG8_MMA(1, 0, At, B0); PG8_BAR; PG8_SCHED;
;             PG8_STAGE(PG8_SB(0, 1), b2, hB, 0);
;             PG8_WAIT_V(6); PG8_BAR; PG8_MMA(1, 1, At, B1); PG8_BAR;
;             PG8_LDB(B0, 1, 0); PG8_SCHED; PG8_LDA(At, 1, 0); PG8_STAGE(PG8_SA(0, 1), a2, hA, 0);
	v_add_u32_e32 v188, 0x14000, v177
	ds_read_b128 v[240:243], v188
	ds_read_b128 v[244:247], v188 offset:1024
	ds_read_b128 v[248:251], v188 offset:2048
	ds_read_b128 v[230:233], v188 offset:3072
	s_and_b64 s[48:49], s[82:83], exec
	s_cselect_b32 s76, s0, s1
	s_cselect_b32 s77, s69, s9
	s_mov_b32 m0, s28
	s_nop 0
	global_load_lds_dwordx4 v152, s[76:77]
	s_add_u32 s48, s76, 0x2000
	s_addc_u32 s49, s77, 0
	s_mov_b32 m0, s29
	s_nop 0
	global_load_lds_dwordx4 v152, s[48:49]
	s_waitcnt vmcnt(10)
	s_barrier
	s_waitcnt lgkmcnt(0)
	s_waitcnt lgkmcnt(3)
	v_mfma_f32_16x16x32_bf16 v[48:51], v[240:243], v[144:147], v[48:51]
	s_waitcnt lgkmcnt(1)
	v_mfma_f32_16x16x32_bf16 v[16:19], v[248:251], v[144:147], v[16:19]
	v_mfma_f32_16x16x32_bf16 v[52:55], v[240:243], v[184:187], v[52:55]
	v_mfma_f32_16x16x32_bf16 v[20:23], v[248:251], v[184:187], v[20:23]
	v_mfma_f32_16x16x32_bf16 v[56:59], v[240:243], v[204:207], v[56:59]
	v_mfma_f32_16x16x32_bf16 v[24:27], v[248:251], v[204:207], v[24:27]
	v_mfma_f32_16x16x32_bf16 v[60:63], v[240:243], v[212:215], v[60:63]
	v_mfma_f32_16x16x32_bf16 v[28:31], v[248:251], v[212:215], v[28:31]
	v_mfma_f32_16x16x32_bf16 v[48:51], v[244:247], v[148:151], v[48:51]
	s_waitcnt lgkmcnt(0)
	v_mfma_f32_16x16x32_bf16 v[16:19], v[230:233], v[148:151], v[16:19]
	v_mfma_f32_16x16x32_bf16 v[52:55], v[244:247], v[200:203], v[52:55]
	v_mfma_f32_16x16x32_bf16 v[20:23], v[230:233], v[200:203], v[20:23]
	v_mfma_f32_16x16x32_bf16 v[56:59], v[244:247], v[208:211], v[56:59]
	v_mfma_f32_16x16x32_bf16 v[24:27], v[230:233], v[208:211], v[24:27]
	v_mfma_f32_16x16x32_bf16 v[60:63], v[244:247], v[236:239], v[60:63]
	v_mfma_f32_16x16x32_bf16 v[28:31], v[230:233], v[236:239], v[28:31]
	s_barrier
	ds_read_b128 v[144:147], v178 offset:16384
	ds_read_b128 v[148:151], v178 offset:17408
	ds_read_b128 v[184:187], v178 offset:18432
	ds_read_b128 v[200:203], v178 offset:19456
	ds_read_b128 v[204:207], v178 offset:20480
	ds_read_b128 v[208:211], v178 offset:21504
	ds_read_b128 v[212:215], v178 offset:22528
	ds_read_b128 v[236:239], v178 offset:23552
	s_mov_b32 m0, s89
	s_nop 0
	global_load_lds_dwordx4 v152, s[80:81]
	s_add_u32 s48, s80, 0x2000
	s_addc_u32 s49, s81, 0
	s_mov_b32 m0, s40
	s_nop 0
	global_load_lds_dwordx4 v152, s[48:49]
	s_waitcnt vmcnt(10)
	s_barrier
	s_waitcnt lgkmcnt(0)
	s_waitcnt lgkmcnt(7)
	v_mfma_f32_16x16x32_bf16 v[100:103], v[128:131], v[144:147], v[100:103]
	v_mfma_f32_16x16x32_bf16 v[64:67], v[136:139], v[144:147], v[64:67]
	s_waitcnt lgkmcnt(5)
	v_mfma_f32_16x16x32_bf16 v[104:107], v[128:131], v[184:187], v[104:107]
	v_mfma_f32_16x16x32_bf16 v[68:71], v[136:139], v[184:187], v[68:71]
	s_waitcnt lgkmcnt(3)
	v_mfma_f32_16x16x32_bf16 v[108:111], v[128:131], v[204:207], v[108:111]
	v_mfma_f32_16x16x32_bf16 v[72:75], v[136:139], v[204:207], v[72:75]
	s_waitcnt lgkmcnt(1)
	v_mfma_f32_16x16x32_bf16 v[112:115], v[128:131], v[212:215], v[112:115]
	v_mfma_f32_16x16x32_bf16 v[76:79], v[136:139], v[212:215], v[76:79]
	v_mfma_f32_16x16x32_bf16 v[100:103], v[132:135], v[148:151], v[100:103]
	v_mfma_f32_16x16x32_bf16 v[64:67], v[140:143], v[148:151], v[64:67]
	v_mfma_f32_16x16x32_bf16 v[104:107], v[132:135], v[200:203], v[104:107]
	v_mfma_f32_16x16x32_bf16 v[68:71], v[140:143], v[200:203], v[68:71]
	v_mfma_f32_16x16x32_bf16 v[108:111], v[132:135], v[208:211], v[108:111]
	v_mfma_f32_16x16x32_bf16 v[72:75], v[140:143], v[208:211], v[72:75]
	s_waitcnt lgkmcnt(0)
	v_mfma_f32_16x16x32_bf16 v[112:115], v[132:135], v[236:239], v[112:115]
	v_mfma_f32_16x16x32_bf16 v[76:79], v[140:143], v[236:239], v[76:79]
	s_barrier
	v_add_u32_e32 v140, 0x18000, v177
	ds_read_b128 v[128:131], v140
	ds_read_b128 v[132:135], v140 offset:1024
	ds_read_b128 v[136:139], v140 offset:2048
	ds_read_b128 v[140:143], v140 offset:3072
	s_add_u32 s48, s76, 0x80000
	s_addc_u32 s49, s77, 0
	s_mov_b32 m0, s41
	s_nop 0
	global_load_lds_dwordx4 v152, s[48:49]
	s_add_u32 s48, s76, 0x82000
	s_addc_u32 s49, s77, 0
	s_mov_b32 m0, s42
	s_nop 0
	global_load_lds_dwordx4 v152, s[48:49]
	s_add_u32 s48, s80, 0x80000
	s_addc_u32 s49, s81, 0
	s_mov_b32 m0, s43
	s_nop 0
	global_load_lds_dwordx4 v152, s[48:49]
	s_add_u32 s48, s80, 0x82000
	s_addc_u32 s49, s81, 0
	s_mov_b32 m0, s92
	s_nop 0
	global_load_lds_dwordx4 v152, s[48:49]
	s_waitcnt vmcnt(12)
	s_barrier
	v_mfma_f32_16x16x32_bf16 v[32:35], v[240:243], v[144:147], v[32:35]
	v_mfma_f32_16x16x32_bf16 v[0:3], v[248:251], v[144:147], v[0:3]
	v_mfma_f32_16x16x32_bf16 v[36:39], v[240:243], v[184:187], v[36:39]
	v_mfma_f32_16x16x32_bf16 v[4:7], v[248:251], v[184:187], v[4:7]
	v_mfma_f32_16x16x32_bf16 v[40:43], v[240:243], v[204:207], v[40:43]
	v_mfma_f32_16x16x32_bf16 v[8:11], v[248:251], v[204:207], v[8:11]
	v_mfma_f32_16x16x32_bf16 v[44:47], v[240:243], v[212:215], v[44:47]
	v_mfma_f32_16x16x32_bf16 v[12:15], v[248:251], v[212:215], v[12:15]
	v_mfma_f32_16x16x32_bf16 v[32:35], v[244:247], v[148:151], v[32:35]
	v_mfma_f32_16x16x32_bf16 v[0:3], v[230:233], v[148:151], v[0:3]
	v_mfma_f32_16x16x32_bf16 v[36:39], v[244:247], v[200:203], v[36:39]
	v_mfma_f32_16x16x32_bf16 v[4:7], v[230:233], v[200:203], v[4:7]
	v_mfma_f32_16x16x32_bf16 v[40:43], v[244:247], v[208:211], v[40:43]
	v_mfma_f32_16x16x32_bf16 v[8:11], v[230:233], v[208:211], v[8:11]
	v_mfma_f32_16x16x32_bf16 v[44:47], v[244:247], v[236:239], v[44:47]
	v_mfma_f32_16x16x32_bf16 v[12:15], v[230:233], v[236:239], v[12:15]
	s_barrier
	ds_read_b128 v[144:147], v178 offset:32768
	ds_read_b128 v[148:151], v178 offset:33792
	ds_read_b128 v[184:187], v178 offset:34816
	ds_read_b128 v[200:203], v178 offset:35840
	ds_read_b128 v[204:207], v178 offset:36864
	ds_read_b128 v[208:211], v178 offset:37888
	ds_read_b128 v[212:215], v178 offset:38912
	ds_read_b128 v[230:233], v178 offset:39936
	s_waitcnt lgkmcnt(8)
	s_waitcnt vmcnt(10)
	s_barrier
; #define PG8_STAGE(bufoff, gbase, hoff, imm) do { _Pragma("unroll") for (int _i = 0; _i < 2; ++_i) { \
;         asm volatile("s_mov_b32 m0, %0\n\ts_nop 0\n\tglobal_load_lds_dwordx4 %1, %2" \
;             :: "s"(lds0 + (unsigned)((bufoff) + _i * 8192)), "v"(voff0), "s"((const char*)(gbase) + (size_t)(hoff) + (size_t)(_i * 8192)) : "memory"); } } while (0)
; #define PG8_LDA(dst, b, h) do { _Pragma("unroll") for (int m = 0; m < 4; ++m) _Pragma("unroll") for (int k = 0; k < 2; ++k) dst[m][k] = *(const LAS bf16x8*)(lds + PG8_SA(b, h) + aoff + m * 2048 + k * 1024); } while (0)
; #define PG8_LDB(dst, b, h) do { _Pragma("unroll") for (int n = 0; n < 2; ++n) _Pragma("unroll") for (int k = 0; k < 2; ++k) dst[n][k] = *(const LAS bf16x8*)(lds + PG8_SB(b, h) + boff + n * 2048 + k * 1024); } while (0)
; #define PG8_MMA(ai, bj, At, Bt) do { __builtin_amdgcn_s_setprio(1); _Pragma("unroll") for (int m = 0; m < 4; ++m) _Pragma("unroll") for (int n = 0; n < 2; ++n) _Pragma("unroll") for (int k = 0; k < 2; ++k) \
;         acc[ai][bj][m][n] = __builtin_amdgcn_mfma_f32_16x16x32_bf16(Bt[n][k], At[m][k], acc[ai][bj][m][n], 0, 0, 0); __builtin_amdgcn_s_setprio(0); } while (0)
; #define PG8_WAIT_V(n) asm volatile("s_waitcnt vmcnt(" #n ")" ::: "memory")
; #define PG8_WAIT_L(n) asm volatile("s_waitcnt lgkmcnt(" #n ")" ::: "memory")
; #define PG8_BAR __builtin_amdgcn_s_barrier()
; #define PG8_SCHED __builtin_amdgcn_sched_barrier(0)
; template <class Epi>
; __device__ __forceinline__ void gemm_phase(LAS unsigned char* lds, const Gemm g, const StaticOrder& S, const Epi& E) {
;     ...
;             PG8_WAIT_L(8); PG8_BAR; PG8_WAIT_L(0); PG8_MMA(0, 0, At, B0); PG8_BAR; PG8_SCHED;
;             PG8_LDB(B1, 1, 1); PG8_STAGE(PG8_SB(1, 0), b2 + KS, 0, 0);
;             PG8_BAR; PG8_WAIT_L(0); PG8_MMA(0, 1, At, B1); PG8_BAR;
;             PG8_LDA(At, 1, 1); PG8_STAGE(PG8_SA(1, 0), a2 + KS, 0, 0);
;             PG8_BAR; PG8_WAIT_L(0); PG8_MMA(1, 0, At, B0); PG8_BAR; PG8_SCHED;
;             PG8_STAGE(PG8_SB(1, 1), b2 + KS, hB, 0);
;             PG8_WAIT_V(6); PG8_BAR; PG8_MMA(1, 1, At, B1); PG8_BAR;
	s_waitcnt lgkmcnt(0)
	s_waitcnt lgkmcnt(7)
	v_mfma_f32_16x16x32_bf16 v[116:119], v[128:131], v[144:147], v[116:119]
	v_mfma_f32_16x16x32_bf16 v[80:83], v[136:139], v[144:147], v[80:83]
	s_waitcnt lgkmcnt(5)
	v_mfma_f32_16x16x32_bf16 v[88:91], v[128:131], v[184:187], v[88:91]
	v_mfma_f32_16x16x32_bf16 v[84:87], v[136:139], v[184:187], v[84:87]
	s_waitcnt lgkmcnt(3)
	v_mfma_f32_16x16x32_bf16 v[120:123], v[128:131], v[204:207], v[120:123]
	v_mfma_f32_16x16x32_bf16 v[92:95], v[136:139], v[204:207], v[92:95]
	s_waitcnt lgkmcnt(1)
	v_mfma_f32_16x16x32_bf16 v[124:127], v[128:131], v[212:215], v[124:127]
	v_mfma_f32_16x16x32_bf16 v[96:99], v[136:139], v[212:215], v[96:99]
	v_mfma_f32_16x16x32_bf16 v[116:119], v[132:135], v[148:151], v[116:119]
	v_mfma_f32_16x16x32_bf16 v[80:83], v[140:143], v[148:151], v[80:83]
	v_mfma_f32_16x16x32_bf16 v[88:91], v[132:135], v[200:203], v[88:91]
	v_mfma_f32_16x16x32_bf16 v[84:87], v[140:143], v[200:203], v[84:87]
	v_mfma_f32_16x16x32_bf16 v[120:123], v[132:135], v[208:211], v[120:123]
	v_mfma_f32_16x16x32_bf16 v[92:95], v[140:143], v[208:211], v[92:95]
	s_waitcnt lgkmcnt(0)
	v_mfma_f32_16x16x32_bf16 v[124:127], v[132:135], v[230:233], v[124:127]
	v_mfma_f32_16x16x32_bf16 v[96:99], v[140:143], v[230:233], v[96:99]
	s_barrier
	v_add_u32_e32 v188, 0x1c000, v177
	ds_read_b128 v[236:239], v188
	ds_read_b128 v[240:243], v188 offset:1024
	ds_read_b128 v[244:247], v188 offset:2048
	ds_read_b128 v[248:251], v188 offset:3072
	s_add_u32 s48, s76, 0x4000
	s_addc_u32 s49, s77, 0
	s_mov_b32 m0, s16
	s_nop 0
	global_load_lds_dwordx4 v152, s[48:49]
	s_add_u32 s48, s76, 0x6000
	s_addc_u32 s49, s77, 0
	s_mov_b32 m0, s17
	s_nop 0
	global_load_lds_dwordx4 v152, s[48:49]
	s_waitcnt vmcnt(10)
	s_barrier
	s_waitcnt lgkmcnt(0)
	s_waitcnt lgkmcnt(3)
	v_mfma_f32_16x16x32_bf16 v[48:51], v[236:239], v[144:147], v[48:51]
	s_waitcnt lgkmcnt(1)
	v_mfma_f32_16x16x32_bf16 v[16:19], v[244:247], v[144:147], v[16:19]
	v_mfma_f32_16x16x32_bf16 v[52:55], v[236:239], v[184:187], v[52:55]
	v_mfma_f32_16x16x32_bf16 v[20:23], v[244:247], v[184:187], v[20:23]
	v_mfma_f32_16x16x32_bf16 v[56:59], v[236:239], v[204:207], v[56:59]
	v_mfma_f32_16x16x32_bf16 v[24:27], v[244:247], v[204:207], v[24:27]
	v_mfma_f32_16x16x32_bf16 v[60:63], v[236:239], v[212:215], v[60:63]
	v_mfma_f32_16x16x32_bf16 v[28:31], v[244:247], v[212:215], v[28:31]
	v_mfma_f32_16x16x32_bf16 v[48:51], v[240:243], v[148:151], v[48:51]
	s_waitcnt lgkmcnt(0)
	v_mfma_f32_16x16x32_bf16 v[16:19], v[248:251], v[148:151], v[16:19]
	v_mfma_f32_16x16x32_bf16 v[52:55], v[240:243], v[200:203], v[52:55]
	v_mfma_f32_16x16x32_bf16 v[20:23], v[248:251], v[200:203], v[20:23]
	v_mfma_f32_16x16x32_bf16 v[56:59], v[240:243], v[208:211], v[56:59]
	v_mfma_f32_16x16x32_bf16 v[24:27], v[248:251], v[208:211], v[24:27]
	v_mfma_f32_16x16x32_bf16 v[60:63], v[240:243], v[230:233], v[60:63]
	v_mfma_f32_16x16x32_bf16 v[28:31], v[248:251], v[230:233], v[28:31]
	s_barrier
	ds_read_b128 v[144:147], v178 offset:49152
	ds_read_b128 v[148:151], v178 offset:50176
	ds_read_b128 v[184:187], v178 offset:51200
	ds_read_b128 v[200:203], v178 offset:52224
	ds_read_b128 v[204:207], v178 offset:53248
	ds_read_b128 v[208:211], v178 offset:54272
	ds_read_b128 v[212:215], v178 offset:55296
	ds_read_b128 v[230:233], v178 offset:56320
	s_add_u32 s48, s80, 0x4000
	s_addc_u32 s49, s81, 0
	s_mov_b32 m0, s24
	s_nop 0
	global_load_lds_dwordx4 v152, s[48:49]
	s_add_u32 s48, s80, 0x6000
	s_addc_u32 s49, s81, 0
	s_mov_b32 m0, s37
	s_nop 0
	global_load_lds_dwordx4 v152, s[48:49]
	s_waitcnt vmcnt(10)
	s_barrier
	s_waitcnt lgkmcnt(0)
	s_waitcnt lgkmcnt(7)
	v_mfma_f32_16x16x32_bf16 v[100:103], v[128:131], v[144:147], v[100:103]
	v_mfma_f32_16x16x32_bf16 v[64:67], v[136:139], v[144:147], v[64:67]
	s_waitcnt lgkmcnt(5)
	v_mfma_f32_16x16x32_bf16 v[104:107], v[128:131], v[184:187], v[104:107]
	v_mfma_f32_16x16x32_bf16 v[68:71], v[136:139], v[184:187], v[68:71]
	s_waitcnt lgkmcnt(3)
	v_mfma_f32_16x16x32_bf16 v[108:111], v[128:131], v[204:207], v[108:111]
	v_mfma_f32_16x16x32_bf16 v[72:75], v[136:139], v[204:207], v[72:75]
	s_waitcnt lgkmcnt(1)
	v_mfma_f32_16x16x32_bf16 v[112:115], v[128:131], v[212:215], v[112:115]
	v_mfma_f32_16x16x32_bf16 v[76:79], v[136:139], v[212:215], v[76:79]
	v_mfma_f32_16x16x32_bf16 v[100:103], v[132:135], v[148:151], v[100:103]
	v_mfma_f32_16x16x32_bf16 v[64:67], v[140:143], v[148:151], v[64:67]
	v_mfma_f32_16x16x32_bf16 v[104:107], v[132:135], v[200:203], v[104:107]
	v_mfma_f32_16x16x32_bf16 v[68:71], v[140:143], v[200:203], v[68:71]
	v_mfma_f32_16x16x32_bf16 v[108:111], v[132:135], v[208:211], v[108:111]
	v_mfma_f32_16x16x32_bf16 v[72:75], v[140:143], v[208:211], v[72:75]
	s_waitcnt lgkmcnt(0)
	v_mfma_f32_16x16x32_bf16 v[112:115], v[132:135], v[230:233], v[112:115]
	v_mfma_f32_16x16x32_bf16 v[76:79], v[140:143], v[230:233], v[76:79]
	s_barrier
	v_add_u32_e32 v140, 0x10000, v177
	ds_read_b128 v[128:131], v140
	ds_read_b128 v[132:135], v140 offset:1024
	ds_read_b128 v[136:139], v140 offset:2048
	ds_read_b128 v[140:143], v140 offset:3072
	s_add_u32 s48, s76, 0x84000
	s_addc_u32 s49, s77, 0
	s_mov_b32 m0, s97
	s_nop 0
	global_load_lds_dwordx4 v152, s[48:49]
	s_add_u32 s48, s76, 0x86000
	s_addc_u32 s49, s77, 0
	s_mov_b32 m0, s38
	s_nop 0
	global_load_lds_dwordx4 v152, s[48:49]
	s_add_u32 s48, s80, 0x84000
	s_addc_u32 s49, s81, 0
	s_mov_b32 m0, s34
	s_nop 0
	global_load_lds_dwordx4 v152, s[48:49]
	s_add_u32 s48, s80, 0x86000
	s_addc_u32 s49, s81, 0
	s_mov_b32 m0, s25
	s_nop 0
	global_load_lds_dwordx4 v152, s[48:49]
	s_waitcnt vmcnt(12)
	s_barrier
	v_mfma_f32_16x16x32_bf16 v[32:35], v[236:239], v[144:147], v[32:35]
	v_mfma_f32_16x16x32_bf16 v[0:3], v[244:247], v[144:147], v[0:3]
	v_mfma_f32_16x16x32_bf16 v[36:39], v[236:239], v[184:187], v[36:39]
	v_mfma_f32_16x16x32_bf16 v[4:7], v[244:247], v[184:187], v[4:7]
	v_mfma_f32_16x16x32_bf16 v[40:43], v[236:239], v[204:207], v[40:43]
	v_mfma_f32_16x16x32_bf16 v[8:11], v[244:247], v[204:207], v[8:11]
	v_mfma_f32_16x16x32_bf16 v[44:47], v[236:239], v[212:215], v[44:47]
	v_mfma_f32_16x16x32_bf16 v[12:15], v[244:247], v[212:215], v[12:15]
	v_mfma_f32_16x16x32_bf16 v[32:35], v[240:243], v[148:151], v[32:35]
	v_mfma_f32_16x16x32_bf16 v[0:3], v[248:251], v[148:151], v[0:3]
	v_mfma_f32_16x16x32_bf16 v[36:39], v[240:243], v[200:203], v[36:39]
	v_mfma_f32_16x16x32_bf16 v[4:7], v[248:251], v[200:203], v[4:7]
	v_mfma_f32_16x16x32_bf16 v[40:43], v[240:243], v[208:211], v[40:43]
	v_mfma_f32_16x16x32_bf16 v[8:11], v[248:251], v[208:211], v[8:11]
	v_mfma_f32_16x16x32_bf16 v[44:47], v[240:243], v[230:233], v[44:47]
	v_mfma_f32_16x16x32_bf16 v[12:15], v[248:251], v[230:233], v[12:15]
	s_add_i32 s71, s71, 2
	s_add_u32 s1, s1, 0x8000
	s_addc_u32 s9, s9, 0
	s_cmp_gt_u32 s71, 29
	s_mov_b64 s[76:77], s[78:79]
	s_barrier
	s_cbranch_scc1 .LBB0_741

; #define LAS __attribute__((address_space(3)))
;     __device__ __forceinline__ void operator()(f32x4 (&acc)[2][2][4][2], const Unit& u, int wr, int wc, int fr, int fq, LAS unsigned char* xl) const {
;     ...
;         asm volatile("s_waitcnt vmcnt(16)" ::: "memory");
;         if (MODE == 1) {
; #pragma unroll
;             for (int ai = 0; ai < 2; ++ai)
; #pragma unroll
;                 for (int m = 0; m < 4; ++m)
; #pragma unroll
;                     for (int n = 0; n < 2; ++n) acc[ai][0][m][n] *= acc[ai][1][m][n];
;         }
;         if (fr >= 14) {
; #pragma unroll
;             for (int ai = 0; ai < 2; ++ai)
; #pragma unroll
;                 for (int s = 0; s < NS; ++s)
; #pragma unroll
;                     for (int n = 0; n < 2; ++n) *(LAS f32x4*)(bnd + (((ai * 2 + wr) * 2 + (fr - 14)) * 256 + s * 128 + chl + 4 * n)) = acc[ai][s][3][n];
;             if (wr == 1) {
; #pragma unroll
;                 for (int s = 0; s < NS; ++s)
; #pragma unroll
;                     for (int n = 0; n < 2; ++n) *(f32x4*)(TAIL + (size_t)(u.pm * 2 + (fr - 14)) * C + (s ? voff : 0) + ch0 + 4 * n) = acc[1][s][3][n];
.LBB0_741:
	s_waitcnt lgkmcnt(0)
	s_waitcnt vmcnt(16)
	v_or_b32_e32 v150, s8, v155
	s_and_saveexec_b64 s[8:9], s[4:5]
	s_cbranch_execz .LBB0_744
	s_andn2_b64 vcc, exec, s[2:3]
	ds_write_b128 v179, v[124:127]
	ds_write_b128 v179, v[96:99] offset:16
	ds_write_b128 v179, v[60:63] offset:512
	ds_write_b128 v179, v[28:31] offset:528
	ds_write_b128 v179, v[112:115] offset:4096
	ds_write_b128 v179, v[76:79] offset:4112
	ds_write_b128 v179, v[44:47] offset:4608
	ds_write_b128 v179, v[12:15] offset:4624
	s_cbranch_vccnz .LBB0_744
	v_lshl_add_u32 v130, s88, 1, v156
	v_mov_b64_e32 v[128:129], s[56:57]
	v_ashrrev_i32_e32 v151, 31, v150
	v_mad_i64_i32 v[128:129], s[0:1], v130, s20, v[128:129]
	v_lshl_add_u64 v[128:129], v[150:151], 2, v[128:129]
	s_mov_b64 s[0:1], 0x5800
	global_store_dwordx4 v[128:129], v[112:115], off
	global_store_dwordx4 v[128:129], v[76:79], off offset:16
	v_lshl_add_u64 v[130:131], v[128:129], 0, s[0:1]
	v_add_co_u32_e32 v128, vcc, 0x5000, v128
	s_nop 1
	v_addc_co_u32_e32 v129, vcc, 0, v129, vcc
	global_store_dwordx4 v[128:129], v[44:47], off offset:2048
	global_store_dwordx4 v[130:131], v[12:15], off offset:16
